# P2 epilogue: the eight row-statistic loads issued before the unit's K loop (registers unused in that phase)
# baseline (speedup 1.0000x reference)
.LBB0_187:
	v_lshl_add_u32 v226, s28, 8, v146
	v_ashrrev_i32_e32 v227, 31, v226
	v_lshl_add_u64 v[226:227], v[226:227], 2, s[8:9]
	global_load_dword v228, v[226:227], off
	global_load_dword v229, v[226:227], off offset:64
	global_load_dword v230, v[226:227], off offset:128
	global_load_dword v231, v[226:227], off offset:192
	global_load_dword v232, v[226:227], off offset:512
	global_load_dword v233, v[226:227], off offset:576
	global_load_dword v234, v[226:227], off offset:640
	global_load_dword v235, v[226:227], off offset:704
	s_ashr_i32 s23, s22, 31
	s_lshl_b64 s[24:25], s[22:23], 21
	s_add_u32 s24, s39, s24
	s_addc_u32 s25, s48, s25
	s_and_b64 s[26:27], s[0:1], exec
	s_cselect_b32 s23, s25, s31
	s_cselect_b32 s73, s24, s30
	s_ashr_i32 s21, s20, 31
	s_lshl_b64 s[26:27], s[20:21], 21
	s_add_u32 s26, s64, s26
	s_addc_u32 s27, s65, s27
	s_and_b64 s[36:37], s[0:1], exec
	s_cselect_b32 s21, s27, s35
	s_cselect_b32 s74, s26, s34
	s_add_u32 s30, s30, 0x100080
	s_addc_u32 s31, s31, 0
	s_add_u32 s75, s34, 0x100
	v_mov_b32_e32 v0, 0
	s_addc_u32 s78, s35, 0
	s_mov_b32 s79, -2
	v_mov_b32_e32 v1, v0
	v_mov_b32_e32 v2, v0
	v_mov_b32_e32 v3, v0
	v_mov_b32_e32 v4, v0
	v_mov_b32_e32 v5, v0
	v_mov_b32_e32 v6, v0
	v_mov_b32_e32 v7, v0
	v_mov_b32_e32 v16, v0
	v_mov_b32_e32 v17, v0
	v_mov_b32_e32 v18, v0
	v_mov_b32_e32 v19, v0
	v_mov_b32_e32 v20, v0
	v_mov_b32_e32 v21, v0
	v_mov_b32_e32 v22, v0
	v_mov_b32_e32 v23, v0
	v_mov_b32_e32 v32, v0
	v_mov_b32_e32 v33, v0
	v_mov_b32_e32 v34, v0
	v_mov_b32_e32 v35, v0
	v_mov_b32_e32 v36, v0
	v_mov_b32_e32 v37, v0
	v_mov_b32_e32 v38, v0
	v_mov_b32_e32 v39, v0
	v_mov_b32_e32 v48, v0
	v_mov_b32_e32 v49, v0
	v_mov_b32_e32 v50, v0
	v_mov_b32_e32 v51, v0
	v_mov_b32_e32 v52, v0
	v_mov_b32_e32 v53, v0
	v_mov_b32_e32 v54, v0
	v_mov_b32_e32 v55, v0
	v_mov_b32_e32 v8, v0
	v_mov_b32_e32 v9, v0
	v_mov_b32_e32 v10, v0
	v_mov_b32_e32 v11, v0
	v_mov_b32_e32 v12, v0
	v_mov_b32_e32 v13, v0
	v_mov_b32_e32 v14, v0
	v_mov_b32_e32 v15, v0
	v_mov_b32_e32 v24, v0
	v_mov_b32_e32 v25, v0
	v_mov_b32_e32 v26, v0
	v_mov_b32_e32 v27, v0
	v_mov_b32_e32 v28, v0
	v_mov_b32_e32 v29, v0
	v_mov_b32_e32 v30, v0
	v_mov_b32_e32 v31, v0
	v_mov_b32_e32 v40, v0
	v_mov_b32_e32 v41, v0
	v_mov_b32_e32 v42, v0
	v_mov_b32_e32 v43, v0
	v_mov_b32_e32 v44, v0
	v_mov_b32_e32 v45, v0
	v_mov_b32_e32 v46, v0
	v_mov_b32_e32 v47, v0
	v_mov_b32_e32 v56, v0
	v_mov_b32_e32 v57, v0
	v_mov_b32_e32 v58, v0
	v_mov_b32_e32 v59, v0
	v_mov_b32_e32 v60, v0
	v_mov_b32_e32 v61, v0
	v_mov_b32_e32 v62, v0
	v_mov_b32_e32 v63, v0
	v_mov_b32_e32 v64, v0
	v_mov_b32_e32 v65, v0
	v_mov_b32_e32 v66, v0
	v_mov_b32_e32 v67, v0
	v_mov_b32_e32 v68, v0
	v_mov_b32_e32 v69, v0
	v_mov_b32_e32 v70, v0
	v_mov_b32_e32 v71, v0
	v_mov_b32_e32 v80, v0
	v_mov_b32_e32 v81, v0
	v_mov_b32_e32 v82, v0
	v_mov_b32_e32 v83, v0
	v_mov_b32_e32 v84, v0
	v_mov_b32_e32 v85, v0
	v_mov_b32_e32 v86, v0
	v_mov_b32_e32 v87, v0
	v_mov_b32_e32 v88, v0
	v_mov_b32_e32 v89, v0
	v_mov_b32_e32 v90, v0
	v_mov_b32_e32 v91, v0
	v_mov_b32_e32 v92, v0
	v_mov_b32_e32 v93, v0
	v_mov_b32_e32 v94, v0
	v_mov_b32_e32 v95, v0
	v_mov_b32_e32 v100, v0
	v_mov_b32_e32 v101, v0
	v_mov_b32_e32 v102, v0
	v_mov_b32_e32 v103, v0
	v_mov_b32_e32 v108, v0
	v_mov_b32_e32 v109, v0
	v_mov_b32_e32 v110, v0
	v_mov_b32_e32 v111, v0
	v_mov_b32_e32 v72, v0
	v_mov_b32_e32 v73, v0
	v_mov_b32_e32 v74, v0
	v_mov_b32_e32 v75, v0
	v_mov_b32_e32 v76, v0
	v_mov_b32_e32 v77, v0
	v_mov_b32_e32 v78, v0
	v_mov_b32_e32 v79, v0
	v_mov_b32_e32 v96, v0
	v_mov_b32_e32 v97, v0
	v_mov_b32_e32 v98, v0
	v_mov_b32_e32 v99, v0
	v_mov_b32_e32 v104, v0
	v_mov_b32_e32 v105, v0
	v_mov_b32_e32 v106, v0
	v_mov_b32_e32 v107, v0
	v_mov_b32_e32 v112, v0
	v_mov_b32_e32 v113, v0
	v_mov_b32_e32 v114, v0
	v_mov_b32_e32 v115, v0
	v_mov_b32_e32 v116, v0
	v_mov_b32_e32 v117, v0
	v_mov_b32_e32 v118, v0
	v_mov_b32_e32 v119, v0
	v_mov_b32_e32 v120, v0
	v_mov_b32_e32 v121, v0
	v_mov_b32_e32 v122, v0
	v_mov_b32_e32 v123, v0
	v_mov_b32_e32 v124, v0
	v_mov_b32_e32 v125, v0
	v_mov_b32_e32 v126, v0
	v_mov_b32_e32 v127, v0

.LBB0_191:
	v_lshl_add_u32 v144, s28, 8, v146
	v_ashrrev_i32_e32 v145, 31, v144
	v_lshl_add_u64 v[154:155], v[144:145], 2, s[8:9]
	v_or_b32_e32 v156, 16, v144
	v_ashrrev_i32_e32 v157, 31, v156
	v_or_b32_e32 v160, 32, v144
	v_lshl_add_u64 v[158:159], v[156:157], 2, s[8:9]
	v_ashrrev_i32_e32 v161, 31, v160
	v_lshl_add_u64 v[162:163], v[160:161], 2, s[8:9]
	v_or_b32_e32 v158, 48, v144
	v_ashrrev_i32_e32 v159, 31, v158
	v_lshl_add_u64 v[162:163], v[158:159], 2, s[8:9]
	s_ashr_i32 s21, s29, 31
	s_lshr_b32 s21, s21, 28
	s_add_i32 s21, s29, s21
	s_add_i32 s23, s29, 15
	s_ashr_i32 s28, s21, 4
	s_cmp_lt_u32 s23, 31
	v_lshl_add_u32 v167, s29, 8, v148
	s_cselect_b64 vcc, -1, 0
	s_ashr_i32 s29, s28, 31
	s_lshl_b64 s[30:31], s[28:29], 27
	s_add_u32 s30, s42, s30
	s_addc_u32 s31, s43, s31
	s_lshl_b32 s21, s28, 12
	v_subrev_u32_e32 v154, s21, v167
	v_cndmask_b32_e32 v174, 1.0, v153, vcc
	v_ashrrev_i32_e32 v155, 31, v154
	v_lshlrev_b64 v[144:145], 13, v[144:145]
	v_lshl_add_u64 v[154:155], v[154:155], 1, s[30:31]
	v_lshl_add_u64 v[144:145], v[154:155], 0, v[144:145]
	v_lshlrev_b64 v[156:157], 13, v[156:157]
	v_lshl_add_u64 v[156:157], v[154:155], 0, v[156:157]
	v_lshlrev_b64 v[160:161], 13, v[160:161]
	v_lshl_add_u64 v[160:161], v[154:155], 0, v[160:161]
	s_waitcnt vmcnt(0)
	v_fmamk_f32 v162, v228, 0x39800000, v152
	v_rsq_f32_e32 v162, v162
	v_fmamk_f32 v163, v229, 0x39800000, v152
	v_fmamk_f32 v164, v230, 0x39800000, v152
	v_rsq_f32_e32 v166, v163
	v_rsq_f32_e32 v167, v164
	v_mul_f32_e32 v162, v174, v162
	v_pk_mul_f32 v[122:123], v[122:123], v[162:163] op_sel_hi:[1,0]
	v_mul_f32_e32 v166, v174, v166
	v_pk_mul_f32 v[126:127], v[126:127], v[162:163] op_sel_hi:[1,0]
	v_pk_mul_f32 v[124:125], v[124:125], v[162:163] op_sel_hi:[1,0]
	v_pk_mul_f32 v[120:121], v[120:121], v[162:163] op_sel_hi:[1,0]
	v_pk_mul_f32 v[110:111], v[110:111], v[162:163] op_sel_hi:[1,0]
	v_pk_mul_f32 v[108:109], v[108:109], v[162:163] op_sel_hi:[1,0]
	v_pk_mul_f32 v[164:165], v[102:103], v[162:163] op_sel_hi:[1,0]
	v_pk_mul_f32 v[162:163], v[100:101], v[162:163] op_sel_hi:[1,0]
	v_cvt_pk_bf16_f32 v100, v124, v125
	v_cvt_pk_bf16_f32 v101, v126, v127
	v_cvt_pk_bf16_f32 v102, v120, v121
	v_cvt_pk_bf16_f32 v103, v122, v123
	v_pk_mul_f32 v[122:123], v[88:89], v[166:167] op_sel_hi:[1,0]
	global_store_dwordx4 v[144:145], v[100:103], off
	v_cvt_pk_bf16_f32 v88, v108, v109
	v_cvt_pk_bf16_f32 v89, v110, v111
	v_pk_mul_f32 v[118:119], v[118:119], v[166:167] op_sel_hi:[1,0]
	v_pk_mul_f32 v[116:117], v[116:117], v[166:167] op_sel_hi:[1,0]
	v_pk_mul_f32 v[120:121], v[90:91], v[166:167] op_sel_hi:[1,0]
	v_cvt_pk_bf16_f32 v90, v162, v163
	v_cvt_pk_bf16_f32 v91, v164, v165
	global_store_dwordx4 v[144:145], v[88:91], off offset:256
	v_mul_f32_e32 v168, v174, v167
	v_pk_mul_f32 v[114:115], v[114:115], v[166:167] op_sel_hi:[1,0]
	v_cvt_pk_bf16_f32 v88, v116, v117
	v_cvt_pk_bf16_f32 v89, v118, v119
	v_pk_mul_f32 v[112:113], v[112:113], v[166:167] op_sel_hi:[1,0]
	v_pk_mul_f32 v[94:95], v[94:95], v[166:167] op_sel_hi:[1,0]
	v_pk_mul_f32 v[92:93], v[92:93], v[166:167] op_sel_hi:[1,0]
	v_cvt_pk_bf16_f32 v90, v112, v113
	v_cvt_pk_bf16_f32 v91, v114, v115
	global_store_dwordx4 v[156:157], v[88:91], off
	v_pk_mul_f32 v[106:107], v[106:107], v[168:169] op_sel_hi:[1,0]
	v_pk_mul_f32 v[104:105], v[104:105], v[168:169] op_sel_hi:[1,0]
	v_cvt_pk_bf16_f32 v88, v92, v93
	v_cvt_pk_bf16_f32 v89, v94, v95
	v_cvt_pk_bf16_f32 v90, v122, v123
	v_cvt_pk_bf16_f32 v91, v120, v121
	global_store_dwordx4 v[156:157], v[88:91], off offset:256
	v_pk_mul_f32 v[84:85], v[84:85], v[168:169] op_sel_hi:[1,0]
	v_pk_mul_f32 v[98:99], v[98:99], v[168:169] op_sel_hi:[1,0]
	v_cvt_pk_bf16_f32 v88, v104, v105
	v_cvt_pk_bf16_f32 v89, v106, v107
	v_pk_mul_f32 v[96:97], v[96:97], v[168:169] op_sel_hi:[1,0]
	v_pk_mul_f32 v[86:87], v[86:87], v[168:169] op_sel_hi:[1,0]
	v_cvt_pk_bf16_f32 v90, v96, v97
	v_cvt_pk_bf16_f32 v91, v98, v99
	global_store_dwordx4 v[160:161], v[88:91], off
	s_nop 1
	v_pk_mul_f32 v[88:89], v[82:83], v[168:169] op_sel_hi:[1,0]
	v_pk_mul_f32 v[82:83], v[80:81], v[168:169] op_sel_hi:[1,0]
	v_cvt_pk_bf16_f32 v80, v84, v85
	v_fmamk_f32 v84, v231, 0x39800000, v152
	v_rsq_f32_e32 v84, v84
	v_cvt_pk_bf16_f32 v81, v86, v87
	v_cvt_pk_bf16_f32 v82, v82, v83
	v_cvt_pk_bf16_f32 v83, v88, v89
	global_store_dwordx4 v[160:161], v[80:83], off offset:256
	s_nop 1
	v_mul_f32_e32 v80, v174, v84
	v_lshlrev_b64 v[82:83], 13, v[158:159]
	v_lshl_add_u64 v[82:83], v[154:155], 0, v[82:83]
	v_pk_mul_f32 v[78:79], v[78:79], v[80:81] op_sel_hi:[1,0]
	v_pk_mul_f32 v[76:77], v[76:77], v[80:81] op_sel_hi:[1,0]
	v_pk_mul_f32 v[84:85], v[74:75], v[80:81] op_sel_hi:[1,0]
	v_pk_mul_f32 v[74:75], v[72:73], v[80:81] op_sel_hi:[1,0]
	v_cvt_pk_bf16_f32 v72, v76, v77
	v_cvt_pk_bf16_f32 v73, v78, v79
	v_pk_mul_f32 v[68:69], v[68:69], v[80:81] op_sel_hi:[1,0]
	v_cvt_pk_bf16_f32 v74, v74, v75
	v_cvt_pk_bf16_f32 v75, v84, v85
	global_store_dwordx4 v[82:83], v[72:75], off
	v_pk_mul_f32 v[70:71], v[70:71], v[80:81] op_sel_hi:[1,0]
	s_nop 0
	v_pk_mul_f32 v[72:73], v[66:67], v[80:81] op_sel_hi:[1,0]
	v_pk_mul_f32 v[66:67], v[64:65], v[80:81] op_sel_hi:[1,0]
	v_cvt_pk_bf16_f32 v64, v68, v69
	v_fmamk_f32 v68, v232, 0x39800000, v152
	v_rsq_f32_e32 v68, v68
	v_cvt_pk_bf16_f32 v65, v70, v71
	v_cvt_pk_bf16_f32 v66, v66, v67
	v_cvt_pk_bf16_f32 v67, v72, v73
	global_store_dwordx4 v[82:83], v[64:67], off offset:256
	s_nop 1
	v_mul_f32_e32 v64, v174, v68
	v_pk_mul_f32 v[60:61], v[60:61], v[64:65] op_sel_hi:[1,0]
	v_pk_mul_f32 v[68:69], v[58:59], v[64:65] op_sel_hi:[1,0]
	v_pk_mul_f32 v[58:59], v[56:57], v[64:65] op_sel_hi:[1,0]
	v_cvt_pk_bf16_f32 v56, v60, v61
	v_add_co_u32_e32 v60, vcc, s69, v144
	v_pk_mul_f32 v[62:63], v[62:63], v[64:65] op_sel_hi:[1,0]
	s_nop 0
	v_addc_co_u32_e32 v61, vcc, 0, v145, vcc
	v_cvt_pk_bf16_f32 v57, v62, v63
	v_pk_mul_f32 v[52:53], v[52:53], v[64:65] op_sel_hi:[1,0]
	v_cvt_pk_bf16_f32 v58, v58, v59
	v_cvt_pk_bf16_f32 v59, v68, v69
	global_store_dwordx4 v[60:61], v[56:59], off
	v_lshl_add_u64 v[66:67], v[144:145], 0, s[4:5]
	v_pk_mul_f32 v[54:55], v[54:55], v[64:65] op_sel_hi:[1,0]
	v_pk_mul_f32 v[56:57], v[50:51], v[64:65] op_sel_hi:[1,0]
	v_pk_mul_f32 v[50:51], v[48:49], v[64:65] op_sel_hi:[1,0]
	v_cvt_pk_bf16_f32 v48, v52, v53
	v_fmamk_f32 v52, v233, 0x39800000, v152
	v_rsq_f32_e32 v52, v52
	v_cvt_pk_bf16_f32 v49, v54, v55
	v_cvt_pk_bf16_f32 v50, v50, v51
	v_cvt_pk_bf16_f32 v51, v56, v57
	global_store_dwordx4 v[66:67], v[48:51], off offset:256
	s_nop 1
	v_mul_f32_e32 v48, v174, v52
	v_pk_mul_f32 v[44:45], v[44:45], v[48:49] op_sel_hi:[1,0]
	v_pk_mul_f32 v[52:53], v[42:43], v[48:49] op_sel_hi:[1,0]
	v_pk_mul_f32 v[42:43], v[40:41], v[48:49] op_sel_hi:[1,0]
	v_cvt_pk_bf16_f32 v40, v44, v45
	v_add_co_u32_e32 v44, vcc, s70, v144
	v_pk_mul_f32 v[46:47], v[46:47], v[48:49] op_sel_hi:[1,0]
	s_nop 0
	v_addc_co_u32_e32 v45, vcc, 0, v145, vcc
	v_cvt_pk_bf16_f32 v41, v46, v47
	v_pk_mul_f32 v[36:37], v[36:37], v[48:49] op_sel_hi:[1,0]
	v_cvt_pk_bf16_f32 v42, v42, v43
	v_cvt_pk_bf16_f32 v43, v52, v53
	global_store_dwordx4 v[44:45], v[40:43], off
	v_lshl_add_u64 v[50:51], v[144:145], 0, s[14:15]
	v_pk_mul_f32 v[38:39], v[38:39], v[48:49] op_sel_hi:[1,0]
	v_pk_mul_f32 v[40:41], v[34:35], v[48:49] op_sel_hi:[1,0]
	v_pk_mul_f32 v[34:35], v[32:33], v[48:49] op_sel_hi:[1,0]
	v_cvt_pk_bf16_f32 v32, v36, v37
	v_fmamk_f32 v36, v234, 0x39800000, v152
	v_rsq_f32_e32 v36, v36
	v_cvt_pk_bf16_f32 v33, v38, v39
	v_cvt_pk_bf16_f32 v34, v34, v35
	v_cvt_pk_bf16_f32 v35, v40, v41
	global_store_dwordx4 v[50:51], v[32:35], off offset:256
	s_nop 1
	v_mul_f32_e32 v32, v174, v36
	v_pk_mul_f32 v[28:29], v[28:29], v[32:33] op_sel_hi:[1,0]
	v_pk_mul_f32 v[36:37], v[26:27], v[32:33] op_sel_hi:[1,0]
	v_pk_mul_f32 v[26:27], v[24:25], v[32:33] op_sel_hi:[1,0]
	v_cvt_pk_bf16_f32 v24, v28, v29
	v_add_co_u32_e32 v28, vcc, s71, v144
	v_pk_mul_f32 v[30:31], v[30:31], v[32:33] op_sel_hi:[1,0]
	s_nop 0
	v_addc_co_u32_e32 v29, vcc, 0, v145, vcc
	v_cvt_pk_bf16_f32 v25, v30, v31
	v_pk_mul_f32 v[20:21], v[20:21], v[32:33] op_sel_hi:[1,0]
	v_cvt_pk_bf16_f32 v26, v26, v27
	v_cvt_pk_bf16_f32 v27, v36, v37
	global_store_dwordx4 v[28:29], v[24:27], off
	v_lshl_add_u64 v[34:35], v[144:145], 0, s[16:17]
	v_pk_mul_f32 v[22:23], v[22:23], v[32:33] op_sel_hi:[1,0]
	v_pk_mul_f32 v[24:25], v[18:19], v[32:33] op_sel_hi:[1,0]
	v_pk_mul_f32 v[18:19], v[16:17], v[32:33] op_sel_hi:[1,0]
	v_cvt_pk_bf16_f32 v16, v20, v21
	v_fmamk_f32 v20, v235, 0x39800000, v152
	v_rsq_f32_e32 v20, v20
	v_cvt_pk_bf16_f32 v17, v22, v23
	v_cvt_pk_bf16_f32 v18, v18, v19
	v_cvt_pk_bf16_f32 v19, v24, v25
	global_store_dwordx4 v[34:35], v[16:19], off offset:256
	s_nop 1
	v_mul_f32_e32 v16, v174, v20
	v_pk_mul_f32 v[12:13], v[12:13], v[16:17] op_sel_hi:[1,0]
	v_pk_mul_f32 v[20:21], v[10:11], v[16:17] op_sel_hi:[1,0]
	v_pk_mul_f32 v[10:11], v[8:9], v[16:17] op_sel_hi:[1,0]
	v_cvt_pk_bf16_f32 v8, v12, v13
	v_add_co_u32_e32 v12, vcc, s72, v144
	v_pk_mul_f32 v[14:15], v[14:15], v[16:17] op_sel_hi:[1,0]
	s_nop 0
	v_addc_co_u32_e32 v13, vcc, 0, v145, vcc
	v_cvt_pk_bf16_f32 v9, v14, v15
	v_lshl_add_u64 v[18:19], v[144:145], 0, s[18:19]
	v_cvt_pk_bf16_f32 v10, v10, v11
	v_cvt_pk_bf16_f32 v11, v20, v21
	global_store_dwordx4 v[12:13], v[8:11], off
	s_andn2_b64 vcc, exec, s[0:1]
	s_mov_b64 s[0:1], -1
	v_pk_mul_f32 v[8:9], v[2:3], v[16:17] op_sel_hi:[1,0]
	v_pk_mul_f32 v[2:3], v[0:1], v[16:17] op_sel_hi:[1,0]
	v_pk_mul_f32 v[6:7], v[6:7], v[16:17] op_sel_hi:[1,0]
	v_pk_mul_f32 v[4:5], v[4:5], v[16:17] op_sel_hi:[1,0]
	s_nop 0
	v_cvt_pk_bf16_f32 v0, v4, v5
	v_cvt_pk_bf16_f32 v1, v6, v7
	v_cvt_pk_bf16_f32 v2, v2, v3
	v_cvt_pk_bf16_f32 v3, v8, v9
	global_store_dwordx4 v[18:19], v[0:3], off offset:256
	s_cbranch_vccnz .LBB0_180
	s_andn2_b64 vcc, exec, s[6:7]
	s_cbranch_vccnz .LBB0_179
	s_barrier
	s_branch .LBB0_179
